# ssm pass-3: F-prefix loop pipelined 4 groups deep; skip-term X loads issued at the chunk top ahead of the gelu stores so no wait sits behind a store
# speedup vs baseline: 1.0092x; 1.0051x over previous
; template <int PASS> __device__ __forceinline__ void ssm_phase(int j, LAS unsigned char* lds, int lane, int wave) { KARGS;
;     ...
;                 for (int cp = 0; cp < c_begin; cp += 8) { f32x2 f[8];
; #pragma unroll
;                     for (int q = 0; q < 8; ++q) f[q] = *(const f32x2*)(Fb + ((size_t)((cp + q) * 128 + g) * 64 + p) * 2);
; #pragma unroll
;                     for (int q = 0; q < 8; ++q) { const float nr = pr * hr - pi * hi + f[q].x, ni = pr * hi + pi * hr + f[q].y; hr = nr; hi = ni; } }
.LBB0_327:
	s_add_i32 s100, s17, -8
	s_add_i32 s101, s12, 0
	s_min_i32 s101, s101, s100
	s_lshl_b32 s101, s101, 7
	s_add_i32 s101, s101, s47
	s_add_i32 s101, s101, s53
	s_add_i32 s68, s101, 0xfffffc80
	s_lshl_b64 s[36:37], s[68:69], 9
	v_lshl_add_u64 v[190:191], v[64:65], 0, s[36:37]
	global_load_dwordx2 v[126:127], v[190:191], off
	s_add_i32 s68, s101, 0xfffffd00
	s_lshl_b64 s[36:37], s[68:69], 9
	v_lshl_add_u64 v[190:191], v[64:65], 0, s[36:37]
	global_load_dwordx2 v[128:129], v[190:191], off
	s_add_i32 s68, s101, 0xfffffd80
	s_lshl_b64 s[36:37], s[68:69], 9
	v_lshl_add_u64 v[190:191], v[64:65], 0, s[36:37]
	global_load_dwordx2 v[130:131], v[190:191], off
	s_add_i32 s68, s101, 0xfffffe00
	s_lshl_b64 s[36:37], s[68:69], 9
	v_lshl_add_u64 v[190:191], v[64:65], 0, s[36:37]
	global_load_dwordx2 v[132:133], v[190:191], off
	s_add_i32 s68, s101, 0xfffffe80
	s_lshl_b64 s[36:37], s[68:69], 9
	v_lshl_add_u64 v[190:191], v[64:65], 0, s[36:37]
	global_load_dwordx2 v[134:135], v[190:191], off
	s_add_i32 s68, s101, 0xffffff00
	s_lshl_b64 s[36:37], s[68:69], 9
	v_lshl_add_u64 v[190:191], v[64:65], 0, s[36:37]
	global_load_dwordx2 v[136:137], v[190:191], off
	s_add_i32 s68, s101, 0xffffff80
	s_lshl_b64 s[36:37], s[68:69], 9
	v_lshl_add_u64 v[190:191], v[64:65], 0, s[36:37]
	global_load_dwordx2 v[138:139], v[190:191], off
	s_mov_b32 s68, s101
	s_lshl_b64 s[36:37], s[68:69], 9
	v_lshl_add_u64 v[190:191], v[64:65], 0, s[36:37]
	global_load_dwordx2 v[140:141], v[190:191], off
	s_add_i32 s101, s12, 8
	s_min_i32 s101, s101, s100
	s_lshl_b32 s101, s101, 7
	s_add_i32 s101, s101, s47
	s_add_i32 s101, s101, s53
	s_add_i32 s68, s101, 0xfffffc80
	s_lshl_b64 s[36:37], s[68:69], 9
	v_lshl_add_u64 v[190:191], v[64:65], 0, s[36:37]
	global_load_dwordx2 v[142:143], v[190:191], off
	s_add_i32 s68, s101, 0xfffffd00
	s_lshl_b64 s[36:37], s[68:69], 9
	v_lshl_add_u64 v[190:191], v[64:65], 0, s[36:37]
	global_load_dwordx2 v[144:145], v[190:191], off
	s_add_i32 s68, s101, 0xfffffd80
	s_lshl_b64 s[36:37], s[68:69], 9
	v_lshl_add_u64 v[190:191], v[64:65], 0, s[36:37]
	global_load_dwordx2 v[146:147], v[190:191], off
	s_add_i32 s68, s101, 0xfffffe00
	s_lshl_b64 s[36:37], s[68:69], 9
	v_lshl_add_u64 v[190:191], v[64:65], 0, s[36:37]
	global_load_dwordx2 v[148:149], v[190:191], off
	s_add_i32 s68, s101, 0xfffffe80
	s_lshl_b64 s[36:37], s[68:69], 9
	v_lshl_add_u64 v[190:191], v[64:65], 0, s[36:37]
	global_load_dwordx2 v[150:151], v[190:191], off
	s_add_i32 s68, s101, 0xffffff00
	s_lshl_b64 s[36:37], s[68:69], 9
	v_lshl_add_u64 v[190:191], v[64:65], 0, s[36:37]
	global_load_dwordx2 v[152:153], v[190:191], off
	s_add_i32 s68, s101, 0xffffff80
	s_lshl_b64 s[36:37], s[68:69], 9
	v_lshl_add_u64 v[190:191], v[64:65], 0, s[36:37]
	global_load_dwordx2 v[154:155], v[190:191], off
	s_mov_b32 s68, s101
	s_lshl_b64 s[36:37], s[68:69], 9
	v_lshl_add_u64 v[190:191], v[64:65], 0, s[36:37]
	global_load_dwordx2 v[156:157], v[190:191], off
	s_add_i32 s101, s12, 16
	s_min_i32 s101, s101, s100
	s_lshl_b32 s101, s101, 7
	s_add_i32 s101, s101, s47
	s_add_i32 s101, s101, s53
	s_add_i32 s68, s101, 0xfffffc80
	s_lshl_b64 s[36:37], s[68:69], 9
	v_lshl_add_u64 v[190:191], v[64:65], 0, s[36:37]
	global_load_dwordx2 v[158:159], v[190:191], off
	s_add_i32 s68, s101, 0xfffffd00
	s_lshl_b64 s[36:37], s[68:69], 9
	v_lshl_add_u64 v[190:191], v[64:65], 0, s[36:37]
	global_load_dwordx2 v[160:161], v[190:191], off
	s_add_i32 s68, s101, 0xfffffd80
	s_lshl_b64 s[36:37], s[68:69], 9
	v_lshl_add_u64 v[190:191], v[64:65], 0, s[36:37]
	global_load_dwordx2 v[162:163], v[190:191], off
	s_add_i32 s68, s101, 0xfffffe00
	s_lshl_b64 s[36:37], s[68:69], 9
	v_lshl_add_u64 v[190:191], v[64:65], 0, s[36:37]
	global_load_dwordx2 v[164:165], v[190:191], off
	s_add_i32 s68, s101, 0xfffffe80
	s_lshl_b64 s[36:37], s[68:69], 9
	v_lshl_add_u64 v[190:191], v[64:65], 0, s[36:37]
	global_load_dwordx2 v[166:167], v[190:191], off
	s_add_i32 s68, s101, 0xffffff00
	s_lshl_b64 s[36:37], s[68:69], 9
	v_lshl_add_u64 v[190:191], v[64:65], 0, s[36:37]
	global_load_dwordx2 v[168:169], v[190:191], off
	s_add_i32 s68, s101, 0xffffff80
	s_lshl_b64 s[36:37], s[68:69], 9
	v_lshl_add_u64 v[190:191], v[64:65], 0, s[36:37]
	global_load_dwordx2 v[170:171], v[190:191], off
	s_mov_b32 s68, s101
	s_lshl_b64 s[36:37], s[68:69], 9
	v_lshl_add_u64 v[190:191], v[64:65], 0, s[36:37]
	global_load_dwordx2 v[172:173], v[190:191], off
	s_add_i32 s101, s12, 24
	s_min_i32 s101, s101, s100
	s_lshl_b32 s101, s101, 7
	s_add_i32 s101, s101, s47
	s_add_i32 s101, s101, s53
	s_add_i32 s68, s101, 0xfffffc80
	s_lshl_b64 s[36:37], s[68:69], 9
	v_lshl_add_u64 v[190:191], v[64:65], 0, s[36:37]
	global_load_dwordx2 v[174:175], v[190:191], off
	s_add_i32 s68, s101, 0xfffffd00
	s_lshl_b64 s[36:37], s[68:69], 9
	v_lshl_add_u64 v[190:191], v[64:65], 0, s[36:37]
	global_load_dwordx2 v[176:177], v[190:191], off
	s_add_i32 s68, s101, 0xfffffd80
	s_lshl_b64 s[36:37], s[68:69], 9
	v_lshl_add_u64 v[190:191], v[64:65], 0, s[36:37]
	global_load_dwordx2 v[178:179], v[190:191], off
	s_add_i32 s68, s101, 0xfffffe00
	s_lshl_b64 s[36:37], s[68:69], 9
	v_lshl_add_u64 v[190:191], v[64:65], 0, s[36:37]
	global_load_dwordx2 v[180:181], v[190:191], off
	s_add_i32 s68, s101, 0xfffffe80
	s_lshl_b64 s[36:37], s[68:69], 9
	v_lshl_add_u64 v[190:191], v[64:65], 0, s[36:37]
	global_load_dwordx2 v[182:183], v[190:191], off
	s_add_i32 s68, s101, 0xffffff00
	s_lshl_b64 s[36:37], s[68:69], 9
	v_lshl_add_u64 v[190:191], v[64:65], 0, s[36:37]
	global_load_dwordx2 v[184:185], v[190:191], off
	s_add_i32 s68, s101, 0xffffff80
	s_lshl_b64 s[36:37], s[68:69], 9
	v_lshl_add_u64 v[190:191], v[64:65], 0, s[36:37]
	global_load_dwordx2 v[186:187], v[190:191], off
	s_mov_b32 s68, s101
	s_lshl_b64 s[36:37], s[68:69], 9
	v_lshl_add_u64 v[190:191], v[64:65], 0, s[36:37]
	global_load_dwordx2 v[188:189], v[190:191], off
	s_waitcnt vmcnt(31)
; template <int PASS> __device__ __forceinline__ void ssm_phase(int j, LAS unsigned char* lds, int lane, int wave) { KARGS;
;     ...
;                 for (int cp = 0; cp < c_begin; cp += 8) { f32x2 f[8];
; #pragma unroll
;                     for (int q = 0; q < 8; ++q) f[q] = *(const f32x2*)(Fb + ((size_t)((cp + q) * 128 + g) * 64 + p) * 2);
; #pragma unroll
;                     for (int q = 0; q < 8; ++q) { const float nr = pr * hr - pi * hi + f[q].x, ni = pr * hi + pi * hr + f[q].y; hr = nr; hi = ni; } }
	v_mul_f32_e32 v8, v6, v0
	v_mul_f32_e32 v9, v7, v1
	v_fma_f32 v0, v4, v0, -v9
	v_fma_f32 v1, v5, v1, v8
	v_add_f32_e32 v0, v0, v126
	v_add_f32_e32 v1, v1, v127
	s_waitcnt vmcnt(30)
	v_mul_f32_e32 v8, v6, v0
	v_mul_f32_e32 v9, v7, v1
	v_fma_f32 v0, v4, v0, -v9
	v_fma_f32 v1, v5, v1, v8
	v_add_f32_e32 v0, v0, v128
	v_add_f32_e32 v1, v1, v129
	s_waitcnt vmcnt(29)
	v_mul_f32_e32 v8, v6, v0
	v_mul_f32_e32 v9, v7, v1
	v_fma_f32 v0, v4, v0, -v9
	v_fma_f32 v1, v5, v1, v8
	v_add_f32_e32 v0, v0, v130
	v_add_f32_e32 v1, v1, v131
	s_waitcnt vmcnt(28)
	v_mul_f32_e32 v8, v6, v0
	v_mul_f32_e32 v9, v7, v1
	v_fma_f32 v0, v4, v0, -v9
	v_fma_f32 v1, v5, v1, v8
	v_add_f32_e32 v0, v0, v132
	v_add_f32_e32 v1, v1, v133
	s_waitcnt vmcnt(27)
	v_mul_f32_e32 v8, v6, v0
	v_mul_f32_e32 v9, v7, v1
	v_fma_f32 v0, v4, v0, -v9
	v_fma_f32 v1, v5, v1, v8
	v_add_f32_e32 v0, v0, v134
	v_add_f32_e32 v1, v1, v135
	s_waitcnt vmcnt(26)
	v_mul_f32_e32 v8, v6, v0
	v_mul_f32_e32 v9, v7, v1
	v_fma_f32 v0, v4, v0, -v9
	v_fma_f32 v1, v5, v1, v8
	v_add_f32_e32 v0, v0, v136
	v_add_f32_e32 v1, v1, v137
	s_waitcnt vmcnt(25)
	v_mul_f32_e32 v8, v6, v0
	v_mul_f32_e32 v9, v7, v1
	v_fma_f32 v0, v4, v0, -v9
	v_fma_f32 v1, v5, v1, v8
	v_add_f32_e32 v0, v0, v138
	v_add_f32_e32 v1, v1, v139
	s_waitcnt vmcnt(24)
	v_mul_f32_e32 v8, v6, v0
	v_mul_f32_e32 v9, v7, v1
	v_fma_f32 v0, v4, v0, -v9
	v_fma_f32 v1, v5, v1, v8
	v_add_f32_e32 v0, v0, v140
	v_add_f32_e32 v1, v1, v141
	s_add_i32 s101, s12, 8
	s_cmp_ge_i32 s101, s17
	s_cbranch_scc1 .Lpf3_end
	s_waitcnt vmcnt(23)
	v_mul_f32_e32 v8, v6, v0
	v_mul_f32_e32 v9, v7, v1
	v_fma_f32 v0, v4, v0, -v9
	v_fma_f32 v1, v5, v1, v8
	v_add_f32_e32 v0, v0, v142
	v_add_f32_e32 v1, v1, v143
	s_waitcnt vmcnt(22)
	v_mul_f32_e32 v8, v6, v0
	v_mul_f32_e32 v9, v7, v1
	v_fma_f32 v0, v4, v0, -v9
	v_fma_f32 v1, v5, v1, v8
	v_add_f32_e32 v0, v0, v144
	v_add_f32_e32 v1, v1, v145
	s_waitcnt vmcnt(21)
	v_mul_f32_e32 v8, v6, v0
	v_mul_f32_e32 v9, v7, v1
	v_fma_f32 v0, v4, v0, -v9
	v_fma_f32 v1, v5, v1, v8
	v_add_f32_e32 v0, v0, v146
	v_add_f32_e32 v1, v1, v147
	s_waitcnt vmcnt(20)
	v_mul_f32_e32 v8, v6, v0
	v_mul_f32_e32 v9, v7, v1
	v_fma_f32 v0, v4, v0, -v9
	v_fma_f32 v1, v5, v1, v8
	v_add_f32_e32 v0, v0, v148
	v_add_f32_e32 v1, v1, v149
	s_waitcnt vmcnt(19)
	v_mul_f32_e32 v8, v6, v0
	v_mul_f32_e32 v9, v7, v1
	v_fma_f32 v0, v4, v0, -v9
	v_fma_f32 v1, v5, v1, v8
	v_add_f32_e32 v0, v0, v150
	v_add_f32_e32 v1, v1, v151
	s_waitcnt vmcnt(18)
	v_mul_f32_e32 v8, v6, v0
	v_mul_f32_e32 v9, v7, v1
	v_fma_f32 v0, v4, v0, -v9
	v_fma_f32 v1, v5, v1, v8
	v_add_f32_e32 v0, v0, v152
	v_add_f32_e32 v1, v1, v153
	s_waitcnt vmcnt(17)
	v_mul_f32_e32 v8, v6, v0
	v_mul_f32_e32 v9, v7, v1
	v_fma_f32 v0, v4, v0, -v9
	v_fma_f32 v1, v5, v1, v8
	v_add_f32_e32 v0, v0, v154
	v_add_f32_e32 v1, v1, v155
	s_waitcnt vmcnt(16)
	v_mul_f32_e32 v8, v6, v0
	v_mul_f32_e32 v9, v7, v1
	v_fma_f32 v0, v4, v0, -v9
	v_fma_f32 v1, v5, v1, v8
	v_add_f32_e32 v0, v0, v156
	v_add_f32_e32 v1, v1, v157
	s_add_i32 s101, s12, 16
	s_cmp_ge_i32 s101, s17
	s_cbranch_scc1 .Lpf3_end
	s_waitcnt vmcnt(15)
	v_mul_f32_e32 v8, v6, v0
	v_mul_f32_e32 v9, v7, v1
	v_fma_f32 v0, v4, v0, -v9
	v_fma_f32 v1, v5, v1, v8
	v_add_f32_e32 v0, v0, v158
	v_add_f32_e32 v1, v1, v159
	s_waitcnt vmcnt(14)
	v_mul_f32_e32 v8, v6, v0
	v_mul_f32_e32 v9, v7, v1
	v_fma_f32 v0, v4, v0, -v9
	v_fma_f32 v1, v5, v1, v8
	v_add_f32_e32 v0, v0, v160
	v_add_f32_e32 v1, v1, v161
	s_waitcnt vmcnt(13)
	v_mul_f32_e32 v8, v6, v0
	v_mul_f32_e32 v9, v7, v1
	v_fma_f32 v0, v4, v0, -v9
	v_fma_f32 v1, v5, v1, v8
	v_add_f32_e32 v0, v0, v162
	v_add_f32_e32 v1, v1, v163
	s_waitcnt vmcnt(12)
	v_mul_f32_e32 v8, v6, v0
	v_mul_f32_e32 v9, v7, v1
	v_fma_f32 v0, v4, v0, -v9
	v_fma_f32 v1, v5, v1, v8
	v_add_f32_e32 v0, v0, v164
	v_add_f32_e32 v1, v1, v165
	s_waitcnt vmcnt(11)
	v_mul_f32_e32 v8, v6, v0
	v_mul_f32_e32 v9, v7, v1
	v_fma_f32 v0, v4, v0, -v9
	v_fma_f32 v1, v5, v1, v8
	v_add_f32_e32 v0, v0, v166
	v_add_f32_e32 v1, v1, v167
	s_waitcnt vmcnt(10)
	v_mul_f32_e32 v8, v6, v0
	v_mul_f32_e32 v9, v7, v1
	v_fma_f32 v0, v4, v0, -v9
	v_fma_f32 v1, v5, v1, v8
	v_add_f32_e32 v0, v0, v168
	v_add_f32_e32 v1, v1, v169
	s_waitcnt vmcnt(9)
	v_mul_f32_e32 v8, v6, v0
	v_mul_f32_e32 v9, v7, v1
	v_fma_f32 v0, v4, v0, -v9
	v_fma_f32 v1, v5, v1, v8
	v_add_f32_e32 v0, v0, v170
	v_add_f32_e32 v1, v1, v171
	s_waitcnt vmcnt(8)
	v_mul_f32_e32 v8, v6, v0
	v_mul_f32_e32 v9, v7, v1
	v_fma_f32 v0, v4, v0, -v9
	v_fma_f32 v1, v5, v1, v8
	v_add_f32_e32 v0, v0, v172
	v_add_f32_e32 v1, v1, v173
	s_add_i32 s101, s12, 24
	s_cmp_ge_i32 s101, s17
	s_cbranch_scc1 .Lpf3_end
	s_waitcnt vmcnt(7)
	v_mul_f32_e32 v8, v6, v0
	v_mul_f32_e32 v9, v7, v1
	v_fma_f32 v0, v4, v0, -v9
	v_fma_f32 v1, v5, v1, v8
	v_add_f32_e32 v0, v0, v174
	v_add_f32_e32 v1, v1, v175
	s_waitcnt vmcnt(6)
	v_mul_f32_e32 v8, v6, v0
	v_mul_f32_e32 v9, v7, v1
	v_fma_f32 v0, v4, v0, -v9
	v_fma_f32 v1, v5, v1, v8
	v_add_f32_e32 v0, v0, v176
	v_add_f32_e32 v1, v1, v177
	s_waitcnt vmcnt(5)
	v_mul_f32_e32 v8, v6, v0
	v_mul_f32_e32 v9, v7, v1
	v_fma_f32 v0, v4, v0, -v9
	v_fma_f32 v1, v5, v1, v8
	v_add_f32_e32 v0, v0, v178
	v_add_f32_e32 v1, v1, v179
	s_waitcnt vmcnt(4)
	v_mul_f32_e32 v8, v6, v0
	v_mul_f32_e32 v9, v7, v1
	v_fma_f32 v0, v4, v0, -v9
	v_fma_f32 v1, v5, v1, v8
	v_add_f32_e32 v0, v0, v180
	v_add_f32_e32 v1, v1, v181
	s_waitcnt vmcnt(3)
	v_mul_f32_e32 v8, v6, v0
	v_mul_f32_e32 v9, v7, v1
	v_fma_f32 v0, v4, v0, -v9
	v_fma_f32 v1, v5, v1, v8
	v_add_f32_e32 v0, v0, v182
	v_add_f32_e32 v1, v1, v183
	s_waitcnt vmcnt(2)
	v_mul_f32_e32 v8, v6, v0
	v_mul_f32_e32 v9, v7, v1
	v_fma_f32 v0, v4, v0, -v9
	v_fma_f32 v1, v5, v1, v8
	v_add_f32_e32 v0, v0, v184
	v_add_f32_e32 v1, v1, v185
	s_waitcnt vmcnt(1)
	v_mul_f32_e32 v8, v6, v0
	v_mul_f32_e32 v9, v7, v1
	v_fma_f32 v0, v4, v0, -v9
	v_fma_f32 v1, v5, v1, v8
	v_add_f32_e32 v0, v0, v186
	v_add_f32_e32 v1, v1, v187
	s_waitcnt vmcnt(0)
	v_mul_f32_e32 v8, v6, v0
	v_mul_f32_e32 v9, v7, v1
	v_fma_f32 v0, v4, v0, -v9
	v_fma_f32 v1, v5, v1, v8
	v_add_f32_e32 v0, v0, v188
	v_add_f32_e32 v1, v1, v189
.Lpf3_end:
	s_add_i32 s12, s12, 32
	s_cmp_ge_i32 s12, s17
	s_cbranch_scc0 .LBB0_327
	s_branch .LBB0_329

; template <int PASS> __device__ __forceinline__ void ssm_phase(int j, LAS unsigned char* lds, int lane, int wave) { KARGS;
;     ...
;             { const int t = 64 * c + lane; float ssq = 0.f;
; #pragma unroll
;               for (int q = 0; q < 8; ++q) { const f32x4 v = *(const f32x4*)(rsp + (size_t)t * 64 + 4 * q); ssq += (v[0] + v[1]) + (v[2] + v[3]); }
;               rsL[lane] = rsqrtf(ssq * (1.0f / D) + EPS); }
;     ...
;                         for (int r = 0; r < 4; ++r) { const int l = 32 * half + 16 * lt + 4 * fq + r; const size_t t = (size_t)(64 * c + l);
;                             const float v = y[r] + dd * X[t * D + ch] * rsL[l];
.LBB0_342:
	s_lshl_b32 s12, s53, 6
	v_or_b32_e32 v52, s12, v60
	v_ashrrev_i32_e32 v53, 31, v52
	v_lshlrev_b64 v[52:53], 8, v[52:53]
	v_lshl_add_u64 v[106:107], s[62:63], 0, v[52:53]
	global_load_dwordx4 v[52:55], v[106:107], off offset:48
	global_load_dwordx4 v[56:59], v[106:107], off offset:32
	global_load_dwordx4 v[98:101], v[106:107], off
	global_load_dwordx4 v[102:105], v[106:107], off offset:16
	s_or_b32 s13, s12, 16
	s_or_b32 s54, s12, 1
	s_or_b32 s55, s12, 2
	s_or_b32 s68, s12, 3
	s_or_b32 s77, s12, 17
	s_or_b32 s80, s12, 18
	s_or_b32 s81, s12, 19
	s_mov_b32 s70, 0
	s_mov_b64 s[4:5], -1
	global_load_dwordx4 v[140:143], v[106:107], off offset:112
	global_load_dwordx4 v[144:147], v[106:107], off offset:96
	global_load_dwordx4 v[148:151], v[106:107], off offset:80
	global_load_dwordx4 v[152:155], v[106:107], off offset:64
	v_add_u32_e32 v211, s15, v77
	v_xor_b32_e32 v195, 0, v63
	v_lshlrev_b32_e32 v195, 4, v195
	v_add3_u32 v195, s15, v195, v73
	v_xor_b32_e32 v196, 1, v63
	v_lshlrev_b32_e32 v196, 4, v196
	v_add3_u32 v196, s15, v196, v73
	v_xor_b32_e32 v197, 2, v63
	v_lshlrev_b32_e32 v197, 4, v197
	v_add3_u32 v197, s15, v197, v73
	v_xor_b32_e32 v198, 3, v63
	v_lshlrev_b32_e32 v198, 4, v198
	v_add3_u32 v198, s15, v198, v73
	v_xor_b32_e32 v199, 4, v63
	v_lshlrev_b32_e32 v199, 4, v199
	v_add3_u32 v199, s15, v199, v73
	v_xor_b32_e32 v200, 5, v63
	v_lshlrev_b32_e32 v200, 4, v200
	v_add3_u32 v200, s15, v200, v73
	v_xor_b32_e32 v201, 6, v63
	v_lshlrev_b32_e32 v201, 4, v201
	v_add3_u32 v201, s15, v201, v73
	v_xor_b32_e32 v202, 7, v63
	v_lshlrev_b32_e32 v202, 4, v202
	v_add3_u32 v202, s15, v202, v73
	v_xor_b32_e32 v203, 8, v63
	v_lshlrev_b32_e32 v203, 4, v203
	v_add3_u32 v203, s15, v203, v73
	v_xor_b32_e32 v204, 9, v63
	v_lshlrev_b32_e32 v204, 4, v204
	v_add3_u32 v204, s15, v204, v73
	v_xor_b32_e32 v205, 10, v63
	v_lshlrev_b32_e32 v205, 4, v205
	v_add3_u32 v205, s15, v205, v73
	v_xor_b32_e32 v206, 11, v63
	v_lshlrev_b32_e32 v206, 4, v206
	v_add3_u32 v206, s15, v206, v73
	v_xor_b32_e32 v207, 12, v63
	v_lshlrev_b32_e32 v207, 4, v207
	v_add3_u32 v207, s15, v207, v73
	v_xor_b32_e32 v208, 13, v63
	v_lshlrev_b32_e32 v208, 4, v208
	v_add3_u32 v208, s15, v208, v73
	v_xor_b32_e32 v209, 14, v63
	v_lshlrev_b32_e32 v209, 4, v209
	v_add3_u32 v209, s15, v209, v73
	v_xor_b32_e32 v210, 15, v63
	v_lshlrev_b32_e32 v210, 4, v210
	v_add3_u32 v210, s15, v210, v73
	v_mov_b32_e32 v134, v72
	v_or_b32_e32 v136, s12, v134
	v_ashrrev_i32_e32 v137, 31, v136
	v_lshlrev_b64 v[136:137], 11, v[136:137]
	v_or_b32_e32 v136, v136, v86
	v_lshl_add_u64 v[136:137], v[136:137], 2, s[60:61]
	global_load_dword v126, v[136:137], off
	v_or_b32_e32 v138, s54, v134
	v_ashrrev_i32_e32 v139, 31, v138
	v_lshlrev_b64 v[138:139], 11, v[138:139]
	v_or_b32_e32 v138, v138, v86
	v_lshl_add_u64 v[138:139], v[138:139], 2, s[60:61]
	global_load_dword v127, v[138:139], off
	v_or_b32_e32 v136, s55, v134
	v_ashrrev_i32_e32 v137, 31, v136
	v_lshlrev_b64 v[136:137], 11, v[136:137]
	v_or_b32_e32 v136, v136, v86
	v_lshl_add_u64 v[136:137], v[136:137], 2, s[60:61]
	global_load_dword v128, v[136:137], off
	v_or_b32_e32 v138, s68, v134
	v_ashrrev_i32_e32 v139, 31, v138
	v_lshlrev_b64 v[138:139], 11, v[138:139]
	v_or_b32_e32 v138, v138, v86
	v_lshl_add_u64 v[138:139], v[138:139], 2, s[60:61]
	global_load_dword v129, v[138:139], off
	v_or_b32_e32 v136, s13, v134
	v_ashrrev_i32_e32 v137, 31, v136
	v_lshlrev_b64 v[136:137], 11, v[136:137]
	v_or_b32_e32 v136, v136, v86
	v_lshl_add_u64 v[136:137], v[136:137], 2, s[60:61]
	global_load_dword v130, v[136:137], off
	v_or_b32_e32 v138, s77, v134
	v_ashrrev_i32_e32 v139, 31, v138
	v_lshlrev_b64 v[138:139], 11, v[138:139]
	v_or_b32_e32 v138, v138, v86
	v_lshl_add_u64 v[138:139], v[138:139], 2, s[60:61]
	global_load_dword v131, v[138:139], off
	v_or_b32_e32 v136, s80, v134
	v_ashrrev_i32_e32 v137, 31, v136
	v_lshlrev_b64 v[136:137], 11, v[136:137]
	v_or_b32_e32 v136, v136, v86
	v_lshl_add_u64 v[136:137], v[136:137], 2, s[60:61]
	global_load_dword v132, v[136:137], off
	v_or_b32_e32 v138, s81, v134
	v_ashrrev_i32_e32 v139, 31, v138
	v_lshlrev_b64 v[138:139], 11, v[138:139]
	v_or_b32_e32 v138, v138, v86
	v_lshl_add_u64 v[138:139], v[138:139], 2, s[60:61]
	global_load_dword v133, v[138:139], off
	v_or_b32_e32 v134, 32, v72
	v_or_b32_e32 v136, s12, v134
	v_ashrrev_i32_e32 v137, 31, v136
	v_lshlrev_b64 v[136:137], 11, v[136:137]
	v_or_b32_e32 v136, v136, v86
	v_lshl_add_u64 v[136:137], v[136:137], 2, s[60:61]
	global_load_dword v236, v[136:137], off
	v_or_b32_e32 v138, s54, v134
	v_ashrrev_i32_e32 v139, 31, v138
	v_lshlrev_b64 v[138:139], 11, v[138:139]
	v_or_b32_e32 v138, v138, v86
	v_lshl_add_u64 v[138:139], v[138:139], 2, s[60:61]
	global_load_dword v237, v[138:139], off
	v_or_b32_e32 v136, s55, v134
	v_ashrrev_i32_e32 v137, 31, v136
	v_lshlrev_b64 v[136:137], 11, v[136:137]
	v_or_b32_e32 v136, v136, v86
	v_lshl_add_u64 v[136:137], v[136:137], 2, s[60:61]
	global_load_dword v238, v[136:137], off
	v_or_b32_e32 v138, s68, v134
	v_ashrrev_i32_e32 v139, 31, v138
	v_lshlrev_b64 v[138:139], 11, v[138:139]
	v_or_b32_e32 v138, v138, v86
	v_lshl_add_u64 v[138:139], v[138:139], 2, s[60:61]
	global_load_dword v239, v[138:139], off
; __device__ __forceinline__ unsigned pk2(float lo, float hi) { const f32x2 v = {lo, hi}; const bf16x2_t b = __builtin_convertvector(v, bf16x2_t); return __builtin_bit_cast(unsigned, b); }
; #define CBAR() asm volatile("s_waitcnt lgkmcnt(0)" ::: "memory")
; template <int PASS> __device__ __forceinline__ void ssm_phase(int j, LAS unsigned char* lds, int lane, int wave) { KARGS;
;     ...
;             { const int t = 64 * c + lane; float ssq = 0.f;
; #pragma unroll
;               for (int q = 0; q < 8; ++q) { const f32x4 v = *(const f32x4*)(rsp + (size_t)t * 64 + 4 * q); ssq += (v[0] + v[1]) + (v[2] + v[3]); }
;               rsL[lane] = rsqrtf(ssq * (1.0f / D) + EPS); }
;             CBAR();
; #pragma unroll 1
;             for (int half = 0; half < 2; ++half) {
; #pragma unroll
;                 for (int lt = 0; lt < 2; ++lt) {
;                     bf16x8 uf = {0, 0, 0, 0, 0, 0, 0, 0};
;                     if (fq < 2) { const int l = 32 * half + 16 * lt + fr; const float rs = rsL[l]; const float* xp = X + (size_t)(64 * c + l) * D + 16 * g + 8 * fq;
;                         const f32x4 x0 = *(const f32x4*)xp * rs, x1 = *(const f32x4*)(xp + 4) * rs;
;                         u32x4 w; w.x = pk2(x0[0], x0[1]); w.y = pk2(x0[2], x0[3]); w.z = pk2(x1[0], x1[1]); w.w = pk2(x1[2], x1[3]); uf = __builtin_bit_cast(bf16x8, w); }
	v_or_b32_e32 v136, s13, v134
	v_ashrrev_i32_e32 v137, 31, v136
	v_lshlrev_b64 v[136:137], 11, v[136:137]
	v_or_b32_e32 v136, v136, v86
	v_lshl_add_u64 v[136:137], v[136:137], 2, s[60:61]
	global_load_dword v240, v[136:137], off
	v_or_b32_e32 v138, s77, v134
	v_ashrrev_i32_e32 v139, 31, v138
	v_lshlrev_b64 v[138:139], 11, v[138:139]
	v_or_b32_e32 v138, v138, v86
	v_lshl_add_u64 v[138:139], v[138:139], 2, s[60:61]
	global_load_dword v241, v[138:139], off
	v_or_b32_e32 v136, s80, v134
	v_ashrrev_i32_e32 v137, 31, v136
	v_lshlrev_b64 v[136:137], 11, v[136:137]
	v_or_b32_e32 v136, v136, v86
	v_lshl_add_u64 v[136:137], v[136:137], 2, s[60:61]
	global_load_dword v242, v[136:137], off
	v_or_b32_e32 v138, s81, v134
	v_ashrrev_i32_e32 v139, 31, v138
	v_lshlrev_b64 v[138:139], 11, v[138:139]
	v_or_b32_e32 v138, v138, v86
	v_lshl_add_u64 v[138:139], v[138:139], 2, s[60:61]
	global_load_dword v243, v[138:139], off
	s_and_saveexec_b64 s[100:101], s[8:9]
	v_mov_b32_e32 v188, v62
	v_or_b32_e32 v188, s12, v188
	v_ashrrev_i32_e32 v189, 31, v188
	v_lshlrev_b64 v[188:189], 13, v[188:189]
	v_lshl_add_u64 v[188:189], v[88:89], 0, v[188:189]
	global_load_dwordx4 v[156:159], v[188:189], off
	global_load_dwordx4 v[160:163], v[188:189], off offset:16
	v_mov_b32_e32 v190, v62
	v_or_b32_e32 v190, s13, v190
	v_ashrrev_i32_e32 v191, 31, v190
	v_lshlrev_b64 v[190:191], 13, v[190:191]
	v_lshl_add_u64 v[190:191], v[88:89], 0, v[190:191]
	global_load_dwordx4 v[164:167], v[190:191], off
	global_load_dwordx4 v[168:171], v[190:191], off offset:16
	v_or_b32_e32 v188, 32, v62
	v_or_b32_e32 v188, s12, v188
	v_ashrrev_i32_e32 v189, 31, v188
	v_lshlrev_b64 v[188:189], 13, v[188:189]
	v_lshl_add_u64 v[188:189], v[88:89], 0, v[188:189]
	global_load_dwordx4 v[172:175], v[188:189], off
	global_load_dwordx4 v[176:179], v[188:189], off offset:16
	v_or_b32_e32 v190, 32, v62
	v_or_b32_e32 v190, s13, v190
	v_ashrrev_i32_e32 v191, 31, v190
	v_lshlrev_b64 v[190:191], 13, v[190:191]
	v_lshl_add_u64 v[190:191], v[88:89], 0, v[190:191]
	global_load_dwordx4 v[180:183], v[190:191], off
	global_load_dwordx4 v[184:187], v[190:191], off offset:16
	s_mov_b64 exec, s[100:101]
	s_waitcnt vmcnt(0)
	v_add_f32_e32 v112, v52, v53
	v_add_f32_e32 v114, v54, v55
	v_mov_b32_e32 v108, v98
	v_mov_b32_e32 v109, v102
	v_mov_b32_e32 v102, v99
	v_pk_add_f32 v[98:99], v[108:109], v[102:103]
	v_mov_b32_e32 v102, v100
	v_mov_b32_e32 v103, v104
	v_mov_b32_e32 v104, v101
	v_pk_add_f32 v[100:101], v[102:103], v[104:105]
	s_nop 0
	v_pk_add_f32 v[98:99], v[98:99], v[100:101]
	s_nop 0
	v_add_f32_e32 v97, 0, v98
	v_add_f32_e32 v108, v97, v99
	v_mov_b32_e32 v98, v57
	v_mov_b32_e32 v99, v58
	v_mov_b32_e32 v57, v59
	v_pk_add_f32 v[56:57], v[98:99], v[56:57]
	s_nop 0
	v_pk_add_f32 v[110:111], v[56:57], v[56:57] op_sel:[0,1] op_sel_hi:[1,0]
	v_mov_b64_e32 v[52:53], v[140:141]
	v_mov_b64_e32 v[54:55], v[142:143]
	v_mov_b64_e32 v[56:57], v[144:145]
	v_mov_b64_e32 v[58:59], v[146:147]
	v_mov_b64_e32 v[98:99], v[148:149]
	v_mov_b64_e32 v[100:101], v[150:151]
	v_mov_b64_e32 v[102:103], v[152:153]
	v_mov_b64_e32 v[104:105], v[154:155]
	v_add_f32_e32 v56, v56, v57
	v_add_f32_e32 v58, v58, v59
	v_mov_b32_e32 v109, v102
	v_mov_b32_e32 v111, v103
	v_mov_b32_e32 v113, v104
	v_mov_b32_e32 v115, v105
	v_pk_add_f32 v[102:103], v[108:109], v[110:111]
	v_pk_add_f32 v[104:105], v[112:113], v[114:115]
	v_mov_b32_e32 v57, v54
	v_pk_add_f32 v[102:103], v[102:103], v[104:105]
	v_mov_b32_e32 v104, v99
	v_mov_b32_e32 v105, v100
	v_mov_b32_e32 v99, v101
	v_pk_add_f32 v[98:99], v[104:105], v[98:99]
	v_pk_add_f32 v[102:103], v[102:103], v[102:103] op_sel:[0,1] op_sel_hi:[1,0]
	v_pk_add_f32 v[98:99], v[98:99], v[98:99] op_sel:[0,1] op_sel_hi:[1,0]
	v_mov_b32_e32 v103, v52
	v_mov_b32_e32 v99, v53
	v_mov_b32_e32 v59, v55
	v_pk_add_f32 v[52:53], v[102:103], v[98:99]
	v_pk_add_f32 v[54:55], v[56:57], v[58:59]
	s_nop 0
	v_pk_add_f32 v[52:53], v[52:53], v[54:55]
	s_nop 0
	v_add_f32_e32 v52, v52, v53
	v_fmamk_f32 v52, v52, 0x3a000000, v223
	v_cmp_gt_f32_e32 vcc, s97, v52
	v_mul_f32_e32 v53, 0x4b800000, v52
	s_nop 0
	v_cndmask_b32_e32 v52, v52, v53, vcc
	v_rsq_f32_e32 v52, v52
	s_nop 0
	v_mul_f32_e32 v53, 0x45800000, v52
	v_cndmask_b32_e32 v52, v52, v53, vcc
	ds_write_b32 v81, v52 offset:16384
	s_waitcnt lgkmcnt(0)
.LBB0_343:
	v_or_b32_e32 v59, s70, v62
	v_mov_b32_e32 v52, 0
	v_lshl_add_u32 v58, v59, 2, s18
	v_mov_b32_e32 v54, 0
	v_mov_b32_e32 v55, 0
	v_mov_b32_e32 v56, 0
	v_mov_b32_e32 v57, 0
	s_and_saveexec_b64 s[10:11], s[8:9]
	s_cbranch_execz .LBB0_345
	v_or_b32_e32 v54, s12, v59
	v_ashrrev_i32_e32 v55, 31, v54
	v_lshlrev_b64 v[54:55], 13, v[54:55]
	v_mov_b64_e32 v[54:55], v[156:157]
	v_mov_b64_e32 v[56:57], v[158:159]
	v_mov_b64_e32 v[98:99], v[160:161]
	v_mov_b64_e32 v[100:101], v[162:163]
	ds_read_b32 v102, v58 offset:16384
	s_waitcnt lgkmcnt(0)
	v_pk_mul_f32 v[56:57], v[56:57], v[102:103] op_sel_hi:[1,0]
	v_pk_mul_f32 v[54:55], v[54:55], v[102:103] op_sel_hi:[1,0]
	v_pk_mul_f32 v[100:101], v[100:101], v[102:103] op_sel_hi:[1,0]
	v_pk_mul_f32 v[98:99], v[98:99], v[102:103] op_sel_hi:[1,0]
	v_cvt_pk_bf16_f32 v54, v54, v55
	v_cvt_pk_bf16_f32 v55, v56, v57
	v_cvt_pk_bf16_f32 v56, v98, v99
	v_cvt_pk_bf16_f32 v57, v100, v101

; #define LAS __attribute__((address_space(3)))
; __device__ __forceinline__ unsigned pk2(float lo, float hi) { const f32x2 v = {lo, hi}; const bf16x2_t b = __builtin_convertvector(v, bf16x2_t); return __builtin_bit_cast(unsigned, b); }
; #define CBAR() asm volatile("s_waitcnt lgkmcnt(0)" ::: "memory")
; template <int PASS> __device__ __forceinline__ void ssm_phase(int j, LAS unsigned char* lds, int lane, int wave) { KARGS;
;     ...
;                         dre[pt] = __builtin_amdgcn_mfma_f32_16x16x32_bf16(uf, bfr[pt], z4, 0, 0, 0); dim[pt] = __builtin_amdgcn_mfma_f32_16x16x32_bf16(uf, bfi[pt], z4, 0, 0, 0); }
;                     asm volatile("s_nop 15\n\ts_nop 15" : "+v"(dre[0]), "+v"(dre[1]), "+v"(dre[2]), "+v"(dre[3]), "+v"(dim[0]), "+v"(dim[1]), "+v"(dim[2]), "+v"(dim[3]));
; #pragma unroll
;                     for (int pt = 0; pt < 4; ++pt)
; #pragma unroll
;                         for (int r = 0; r < 4; ++r) *(LAS unsigned*)(buL + (16 * lt + 4 * fq + r) * 256 + 4 * (16 * pt + fr)) = pk2(dre[pt][r], dim[pt][r]);
;                 }
;                 CBAR();
; #pragma unroll 1
;                 for (int l8 = 0; l8 < 32; l8 += 8) {
;                     unsigned w[8];
; #pragma unroll
;                     for (int q = 0; q < 8; ++q) w[q] = *(const LAS unsigned*)(buL + (l8 + q) * 256 + 4 * p);
; #pragma unroll
;                     for (int q = 0; q < 8; ++q) {
;                         const float nr = abr * hr - abi * hi + bflo(w[q]), ni = abr * hi + abi * hr + bfhi(w[q]); hr = nr; hi = ni;
;                         if (PASS == 3) *(LAS unsigned*)(hL + (l8 + q) * 256 + ((((p >> 2) ^ ((l8 + q) & 15))) << 4) + (p & 3) * 4) = pk2(hr, hi);
;                     }
;                 }
.LBB0_347:
	s_or_b64 exec, exec, s[10:11]
	s_nop 0
	v_mfma_f32_16x16x32_bf16 v[56:59], v[52:55], v[12:15], 0
	s_xor_b64 s[10:11], s[4:5], -1
	s_mov_b32 s4, -8
	v_mfma_f32_16x16x32_bf16 v[98:101], v[52:55], v[8:11], 0
	v_mfma_f32_16x16x32_bf16 v[102:105], v[52:55], v[16:19], 0
	v_mfma_f32_16x16x32_bf16 v[106:109], v[52:55], v[4:7], 0
	v_mfma_f32_16x16x32_bf16 v[110:113], v[52:55], v[28:31], 0
	v_mfma_f32_16x16x32_bf16 v[114:117], v[52:55], v[24:27], 0
	v_mfma_f32_16x16x32_bf16 v[118:121], v[52:55], v[32:35], 0
	v_mfma_f32_16x16x32_bf16 v[52:55], v[52:55], v[20:23], 0
	s_nop 15
	s_nop 15
	s_nop 1
	v_cvt_pk_bf16_f32 v56, v56, v98
	s_nop 0
	v_cvt_pk_bf16_f32 v97, v102, v106
	v_add_u32_e32 v98, 0x3000, v96
	v_cvt_pk_bf16_f32 v57, v57, v99
	ds_write2_b32 v98, v56, v97 offset1:16
	v_cvt_pk_bf16_f32 v56, v103, v107
	v_cvt_pk_bf16_f32 v58, v58, v100
	ds_write2_b32 v98, v57, v56 offset0:64 offset1:80
	v_cvt_pk_bf16_f32 v56, v104, v108
	v_cvt_pk_bf16_f32 v59, v59, v101
	ds_write2_b32 v98, v58, v56 offset0:128 offset1:144
	v_cvt_pk_bf16_f32 v56, v105, v109
	ds_write2_b32 v98, v59, v56 offset0:192 offset1:208
	v_cvt_pk_bf16_f32 v56, v110, v114
	v_cvt_pk_bf16_f32 v52, v118, v52
	v_cvt_pk_bf16_f32 v57, v111, v115
	ds_write2_b32 v98, v56, v52 offset0:32 offset1:48
	v_cvt_pk_bf16_f32 v52, v119, v53
	v_cvt_pk_bf16_f32 v58, v112, v116
	ds_write2_b32 v98, v57, v52 offset0:96 offset1:112
	v_cvt_pk_bf16_f32 v52, v120, v54
	v_cvt_pk_bf16_f32 v59, v113, v117
	ds_write2_b32 v98, v58, v52 offset0:160 offset1:176
	v_cvt_pk_bf16_f32 v52, v121, v55
	ds_write2_b32 v98, v59, v52 offset0:224 offset1:240
	s_waitcnt lgkmcnt(0)
	ds_read2st64_b32 v[52:53], v211 offset0:0 offset1:1
	ds_read2st64_b32 v[54:55], v211 offset0:2 offset1:3
	ds_read2st64_b32 v[56:57], v211 offset0:4 offset1:5
	ds_read2st64_b32 v[58:59], v211 offset0:6 offset1:7
	s_waitcnt lgkmcnt(0)
	ds_read2st64_b32 v[98:99], v211 offset0:8 offset1:9
	ds_read2st64_b32 v[100:101], v211 offset0:10 offset1:11
	ds_read2st64_b32 v[102:103], v211 offset0:12 offset1:13
	ds_read2st64_b32 v[104:105], v211 offset0:14 offset1:15
	v_mul_f32_e32 v106, v84, v0
	v_mul_f32_e32 v107, v85, v1
	v_lshlrev_b32_e32 v108, 16, v52
	v_and_b32_e32 v109, 0xffff0000, v52
	v_fma_f32 v0, v2, v0, -v107
	v_fma_f32 v1, v3, v1, v106
	v_add_f32_e32 v0, v0, v108
	v_add_f32_e32 v1, v1, v109
	v_cvt_pk_bf16_f32 v110, v0, v1
	ds_write_b32 v195, v110
	v_mul_f32_e32 v111, v84, v0
	v_mul_f32_e32 v112, v85, v1
	v_lshlrev_b32_e32 v113, 16, v53
	v_and_b32_e32 v114, 0xffff0000, v53
	v_fma_f32 v0, v2, v0, -v112
	v_fma_f32 v1, v3, v1, v111
	v_add_f32_e32 v0, v0, v113
	v_add_f32_e32 v1, v1, v114
	v_cvt_pk_bf16_f32 v115, v0, v1
	ds_write_b32 v196, v115 offset:256
	v_mul_f32_e32 v106, v84, v0
	v_mul_f32_e32 v107, v85, v1
	v_lshlrev_b32_e32 v108, 16, v54
	v_and_b32_e32 v109, 0xffff0000, v54
	v_fma_f32 v0, v2, v0, -v107
	v_fma_f32 v1, v3, v1, v106
	v_add_f32_e32 v0, v0, v108
	v_add_f32_e32 v1, v1, v109
	v_cvt_pk_bf16_f32 v110, v0, v1
	ds_write_b32 v197, v110 offset:512
	v_mul_f32_e32 v111, v84, v0
	v_mul_f32_e32 v112, v85, v1
	v_lshlrev_b32_e32 v113, 16, v55
	v_and_b32_e32 v114, 0xffff0000, v55
	v_fma_f32 v0, v2, v0, -v112
	v_fma_f32 v1, v3, v1, v111
	v_add_f32_e32 v0, v0, v113
	v_add_f32_e32 v1, v1, v114
	v_cvt_pk_bf16_f32 v115, v0, v1
	ds_write_b32 v198, v115 offset:768
	v_mul_f32_e32 v106, v84, v0
	v_mul_f32_e32 v107, v85, v1
	v_lshlrev_b32_e32 v108, 16, v56
	v_and_b32_e32 v109, 0xffff0000, v56
	v_fma_f32 v0, v2, v0, -v107
	v_fma_f32 v1, v3, v1, v106
	v_add_f32_e32 v0, v0, v108
	v_add_f32_e32 v1, v1, v109
	v_cvt_pk_bf16_f32 v110, v0, v1
	ds_write_b32 v199, v110 offset:1024
	v_mul_f32_e32 v111, v84, v0
	v_mul_f32_e32 v112, v85, v1
	v_lshlrev_b32_e32 v113, 16, v57
	v_and_b32_e32 v114, 0xffff0000, v57
	v_fma_f32 v0, v2, v0, -v112
	v_fma_f32 v1, v3, v1, v111
	v_add_f32_e32 v0, v0, v113
	v_add_f32_e32 v1, v1, v114
	v_cvt_pk_bf16_f32 v115, v0, v1
	ds_write_b32 v200, v115 offset:1280
	v_mul_f32_e32 v106, v84, v0
	v_mul_f32_e32 v107, v85, v1
	v_lshlrev_b32_e32 v108, 16, v58
	v_and_b32_e32 v109, 0xffff0000, v58
	v_fma_f32 v0, v2, v0, -v107
	v_fma_f32 v1, v3, v1, v106
	v_add_f32_e32 v0, v0, v108
	v_add_f32_e32 v1, v1, v109
	v_cvt_pk_bf16_f32 v110, v0, v1
	ds_write_b32 v201, v110 offset:1536
	v_mul_f32_e32 v111, v84, v0
	v_mul_f32_e32 v112, v85, v1
	v_lshlrev_b32_e32 v113, 16, v59
	v_and_b32_e32 v114, 0xffff0000, v59
	v_fma_f32 v0, v2, v0, -v112
	v_fma_f32 v1, v3, v1, v111
	v_add_f32_e32 v0, v0, v113
	v_add_f32_e32 v1, v1, v114
	v_cvt_pk_bf16_f32 v115, v0, v1
	ds_write_b32 v202, v115 offset:1792
	s_waitcnt lgkmcnt(8)
; #define LAS __attribute__((address_space(3)))
; __device__ __forceinline__ unsigned pk2(float lo, float hi) { const f32x2 v = {lo, hi}; const bf16x2_t b = __builtin_convertvector(v, bf16x2_t); return __builtin_bit_cast(unsigned, b); }
; template <int PASS> __device__ __forceinline__ void ssm_phase(int j, LAS unsigned char* lds, int lane, int wave) { KARGS;
;     ...
;                 for (int l8 = 0; l8 < 32; l8 += 8) {
;                     unsigned w[8];
; #pragma unroll
;                     for (int q = 0; q < 8; ++q) w[q] = *(const LAS unsigned*)(buL + (l8 + q) * 256 + 4 * p);
; #pragma unroll
;                     for (int q = 0; q < 8; ++q) {
;                         const float nr = abr * hr - abi * hi + bflo(w[q]), ni = abr * hi + abi * hr + bfhi(w[q]); hr = nr; hi = ni;
;                         if (PASS == 3) *(LAS unsigned*)(hL + (l8 + q) * 256 + ((((p >> 2) ^ ((l8 + q) & 15))) << 4) + (p & 3) * 4) = pk2(hr, hi);
;                     }
;                 }
	ds_read2st64_b32 v[52:53], v211 offset0:16 offset1:17
	ds_read2st64_b32 v[54:55], v211 offset0:18 offset1:19
	ds_read2st64_b32 v[56:57], v211 offset0:20 offset1:21
	ds_read2st64_b32 v[58:59], v211 offset0:22 offset1:23
	v_mul_f32_e32 v106, v84, v0
	v_mul_f32_e32 v107, v85, v1
	v_lshlrev_b32_e32 v108, 16, v98
	v_and_b32_e32 v109, 0xffff0000, v98
	v_fma_f32 v0, v2, v0, -v107
	v_fma_f32 v1, v3, v1, v106
	v_add_f32_e32 v0, v0, v108
	v_add_f32_e32 v1, v1, v109
	v_cvt_pk_bf16_f32 v110, v0, v1
	ds_write_b32 v203, v110 offset:2048
	v_mul_f32_e32 v111, v84, v0
	v_mul_f32_e32 v112, v85, v1
	v_lshlrev_b32_e32 v113, 16, v99
	v_and_b32_e32 v114, 0xffff0000, v99
	v_fma_f32 v0, v2, v0, -v112
	v_fma_f32 v1, v3, v1, v111
	v_add_f32_e32 v0, v0, v113
	v_add_f32_e32 v1, v1, v114
	v_cvt_pk_bf16_f32 v115, v0, v1
	ds_write_b32 v204, v115 offset:2304
	v_mul_f32_e32 v106, v84, v0
	v_mul_f32_e32 v107, v85, v1
	v_lshlrev_b32_e32 v108, 16, v100
	v_and_b32_e32 v109, 0xffff0000, v100
	v_fma_f32 v0, v2, v0, -v107
	v_fma_f32 v1, v3, v1, v106
	v_add_f32_e32 v0, v0, v108
	v_add_f32_e32 v1, v1, v109
	v_cvt_pk_bf16_f32 v110, v0, v1
	ds_write_b32 v205, v110 offset:2560
	v_mul_f32_e32 v111, v84, v0
	v_mul_f32_e32 v112, v85, v1
	v_lshlrev_b32_e32 v113, 16, v101
	v_and_b32_e32 v114, 0xffff0000, v101
	v_fma_f32 v0, v2, v0, -v112
	v_fma_f32 v1, v3, v1, v111
	v_add_f32_e32 v0, v0, v113
	v_add_f32_e32 v1, v1, v114
	v_cvt_pk_bf16_f32 v115, v0, v1
	ds_write_b32 v206, v115 offset:2816
	v_mul_f32_e32 v106, v84, v0
	v_mul_f32_e32 v107, v85, v1
	v_lshlrev_b32_e32 v108, 16, v102
	v_and_b32_e32 v109, 0xffff0000, v102
	v_fma_f32 v0, v2, v0, -v107
	v_fma_f32 v1, v3, v1, v106
	v_add_f32_e32 v0, v0, v108
	v_add_f32_e32 v1, v1, v109
	v_cvt_pk_bf16_f32 v110, v0, v1
	ds_write_b32 v207, v110 offset:3072
	v_mul_f32_e32 v111, v84, v0
	v_mul_f32_e32 v112, v85, v1
	v_lshlrev_b32_e32 v113, 16, v103
	v_and_b32_e32 v114, 0xffff0000, v103
	v_fma_f32 v0, v2, v0, -v112
	v_fma_f32 v1, v3, v1, v111
	v_add_f32_e32 v0, v0, v113
	v_add_f32_e32 v1, v1, v114
	v_cvt_pk_bf16_f32 v115, v0, v1
	ds_write_b32 v208, v115 offset:3328
	v_mul_f32_e32 v106, v84, v0
	v_mul_f32_e32 v107, v85, v1
	v_lshlrev_b32_e32 v108, 16, v104
	v_and_b32_e32 v109, 0xffff0000, v104
	v_fma_f32 v0, v2, v0, -v107
	v_fma_f32 v1, v3, v1, v106
	v_add_f32_e32 v0, v0, v108
	v_add_f32_e32 v1, v1, v109
	v_cvt_pk_bf16_f32 v110, v0, v1
	ds_write_b32 v209, v110 offset:3584
	v_mul_f32_e32 v111, v84, v0
	v_mul_f32_e32 v112, v85, v1
	v_lshlrev_b32_e32 v113, 16, v105
	v_and_b32_e32 v114, 0xffff0000, v105
	v_fma_f32 v0, v2, v0, -v112
	v_fma_f32 v1, v3, v1, v111
	v_add_f32_e32 v0, v0, v113
	v_add_f32_e32 v1, v1, v114
	v_cvt_pk_bf16_f32 v115, v0, v1
	ds_write_b32 v210, v115 offset:3840
	s_waitcnt lgkmcnt(8)
	ds_read2st64_b32 v[98:99], v211 offset0:24 offset1:25
	ds_read2st64_b32 v[100:101], v211 offset0:26 offset1:27
	ds_read2st64_b32 v[102:103], v211 offset0:28 offset1:29
	ds_read2st64_b32 v[104:105], v211 offset0:30 offset1:31
	v_mul_f32_e32 v106, v84, v0
	v_mul_f32_e32 v107, v85, v1
	v_lshlrev_b32_e32 v108, 16, v52
	v_and_b32_e32 v109, 0xffff0000, v52
	v_fma_f32 v0, v2, v0, -v107
	v_fma_f32 v1, v3, v1, v106
	v_add_f32_e32 v0, v0, v108
	v_add_f32_e32 v1, v1, v109
	v_cvt_pk_bf16_f32 v110, v0, v1
	ds_write_b32 v195, v110 offset:4096
	v_mul_f32_e32 v111, v84, v0
	v_mul_f32_e32 v112, v85, v1
	v_lshlrev_b32_e32 v113, 16, v53
	v_and_b32_e32 v114, 0xffff0000, v53
	v_fma_f32 v0, v2, v0, -v112
	v_fma_f32 v1, v3, v1, v111
	v_add_f32_e32 v0, v0, v113
	v_add_f32_e32 v1, v1, v114
	v_cvt_pk_bf16_f32 v115, v0, v1
	ds_write_b32 v196, v115 offset:4352
	v_mul_f32_e32 v106, v84, v0
	v_mul_f32_e32 v107, v85, v1
	v_lshlrev_b32_e32 v108, 16, v54
	v_and_b32_e32 v109, 0xffff0000, v54
	v_fma_f32 v0, v2, v0, -v107
	v_fma_f32 v1, v3, v1, v106
	v_add_f32_e32 v0, v0, v108
	v_add_f32_e32 v1, v1, v109
	v_cvt_pk_bf16_f32 v110, v0, v1
	ds_write_b32 v197, v110 offset:4608
	v_mul_f32_e32 v111, v84, v0
	v_mul_f32_e32 v112, v85, v1
	v_lshlrev_b32_e32 v113, 16, v55
	v_and_b32_e32 v114, 0xffff0000, v55
	v_fma_f32 v0, v2, v0, -v112
	v_fma_f32 v1, v3, v1, v111
	v_add_f32_e32 v0, v0, v113
	v_add_f32_e32 v1, v1, v114
	v_cvt_pk_bf16_f32 v115, v0, v1
	ds_write_b32 v198, v115 offset:4864
	v_mul_f32_e32 v106, v84, v0
	v_mul_f32_e32 v107, v85, v1
	v_lshlrev_b32_e32 v108, 16, v56
	v_and_b32_e32 v109, 0xffff0000, v56
	v_fma_f32 v0, v2, v0, -v107
	v_fma_f32 v1, v3, v1, v106
	v_add_f32_e32 v0, v0, v108
	v_add_f32_e32 v1, v1, v109
	v_cvt_pk_bf16_f32 v110, v0, v1
	ds_write_b32 v199, v110 offset:5120
	v_mul_f32_e32 v111, v84, v0
	v_mul_f32_e32 v112, v85, v1
	v_lshlrev_b32_e32 v113, 16, v57
	v_and_b32_e32 v114, 0xffff0000, v57
	v_fma_f32 v0, v2, v0, -v112
	v_fma_f32 v1, v3, v1, v111
	v_add_f32_e32 v0, v0, v113
	v_add_f32_e32 v1, v1, v114
	v_cvt_pk_bf16_f32 v115, v0, v1
	ds_write_b32 v200, v115 offset:5376
	v_mul_f32_e32 v106, v84, v0
	v_mul_f32_e32 v107, v85, v1
	v_lshlrev_b32_e32 v108, 16, v58
	v_and_b32_e32 v109, 0xffff0000, v58
	v_fma_f32 v0, v2, v0, -v107
	v_fma_f32 v1, v3, v1, v106
	v_add_f32_e32 v0, v0, v108
	v_add_f32_e32 v1, v1, v109
	v_cvt_pk_bf16_f32 v110, v0, v1
	ds_write_b32 v201, v110 offset:5632
	v_mul_f32_e32 v111, v84, v0
	v_mul_f32_e32 v112, v85, v1
	v_lshlrev_b32_e32 v113, 16, v59
	v_and_b32_e32 v114, 0xffff0000, v59
	v_fma_f32 v0, v2, v0, -v112
	v_fma_f32 v1, v3, v1, v111
	v_add_f32_e32 v0, v0, v113
	v_add_f32_e32 v1, v1, v114
	v_cvt_pk_bf16_f32 v115, v0, v1
	ds_write_b32 v202, v115 offset:5888
	s_waitcnt lgkmcnt(8)
; #define LAS __attribute__((address_space(3)))
; __device__ __forceinline__ unsigned f2bf(float f) { unsigned u = __builtin_bit_cast(unsigned, f); return (u + 0x7fffu + ((u >> 16) & 1u)) >> 16; }
; __device__ __forceinline__ unsigned pk2(float lo, float hi) { const f32x2 v = {lo, hi}; const bf16x2_t b = __builtin_convertvector(v, bf16x2_t); return __builtin_bit_cast(unsigned, b); }
; __device__ __forceinline__ float gelu_tanh(float v) { const float z = 0.7978845608028654f * (v + 0.044715f * v * v * v); return v * (1.0f - 1.0f / (1.0f + __expf(2.0f * z))); }
; #define CBAR() asm volatile("s_waitcnt lgkmcnt(0)" ::: "memory")
; template <int PASS> __device__ __forceinline__ void ssm_phase(int j, LAS unsigned char* lds, int lane, int wave) { KARGS;
;     ...
;                 for (int l8 = 0; l8 < 32; l8 += 8) {
;                     unsigned w[8];
; #pragma unroll
;                     for (int q = 0; q < 8; ++q) w[q] = *(const LAS unsigned*)(buL + (l8 + q) * 256 + 4 * p);
; #pragma unroll
;                     for (int q = 0; q < 8; ++q) {
;                         const float nr = abr * hr - abi * hi + bflo(w[q]), ni = abr * hi + abi * hr + bfhi(w[q]); hr = nr; hi = ni;
;                         if (PASS == 3) *(LAS unsigned*)(hL + (l8 + q) * 256 + ((((p >> 2) ^ ((l8 + q) & 15))) << 4) + (p & 3) * 4) = pk2(hr, hi);
;                     }
;                 }
;                 CBAR();
;                 if (PASS == 3) {
; #pragma unroll
;                     for (int lt = 0; lt < 2; ++lt) {
;                         f32x4 y = {0.f, 0.f, 0.f, 0.f};
; #pragma unroll
;                         for (int ks = 0; ks < 4; ++ks) { const bf16x8 hf = *(const LAS bf16x8*)(hL + (16 * lt + fr) * 256 + (((4 * ks + fq) ^ fr) << 4)); y = __builtin_amdgcn_mfma_f32_16x16x32_bf16(hf, cf[ks], y, 0, 0, 0); }
;                         asm volatile("s_nop 15\n\ts_nop 15" : "+v"(y));
;                         const int ch = 16 * g + fr;
; #pragma unroll
;                         for (int r = 0; r < 4; ++r) { const int l = 32 * half + 16 * lt + 4 * fq + r; const size_t t = (size_t)(64 * c + l);
;                             const float v = y[r] + dd * X[t * D + ch] * rsL[l];
;                             GL[t * D + ch] = (bf16_t)f2bf(gelu_tanh(v)); }
	v_mul_f32_e32 v106, v84, v0
	v_mul_f32_e32 v107, v85, v1
	v_lshlrev_b32_e32 v108, 16, v98
	v_and_b32_e32 v109, 0xffff0000, v98
	v_fma_f32 v0, v2, v0, -v107
	v_fma_f32 v1, v3, v1, v106
	v_add_f32_e32 v0, v0, v108
	v_add_f32_e32 v1, v1, v109
	v_cvt_pk_bf16_f32 v110, v0, v1
	ds_write_b32 v203, v110 offset:6144
	v_mul_f32_e32 v111, v84, v0
	v_mul_f32_e32 v112, v85, v1
	v_lshlrev_b32_e32 v113, 16, v99
	v_and_b32_e32 v114, 0xffff0000, v99
	v_fma_f32 v0, v2, v0, -v112
	v_fma_f32 v1, v3, v1, v111
	v_add_f32_e32 v0, v0, v113
	v_add_f32_e32 v1, v1, v114
	v_cvt_pk_bf16_f32 v115, v0, v1
	ds_write_b32 v204, v115 offset:6400
	v_mul_f32_e32 v106, v84, v0
	v_mul_f32_e32 v107, v85, v1
	v_lshlrev_b32_e32 v108, 16, v100
	v_and_b32_e32 v109, 0xffff0000, v100
	v_fma_f32 v0, v2, v0, -v107
	v_fma_f32 v1, v3, v1, v106
	v_add_f32_e32 v0, v0, v108
	v_add_f32_e32 v1, v1, v109
	v_cvt_pk_bf16_f32 v110, v0, v1
	ds_write_b32 v205, v110 offset:6656
	v_mul_f32_e32 v111, v84, v0
	v_mul_f32_e32 v112, v85, v1
	v_lshlrev_b32_e32 v113, 16, v101
	v_and_b32_e32 v114, 0xffff0000, v101
	v_fma_f32 v0, v2, v0, -v112
	v_fma_f32 v1, v3, v1, v111
	v_add_f32_e32 v0, v0, v113
	v_add_f32_e32 v1, v1, v114
	v_cvt_pk_bf16_f32 v115, v0, v1
	ds_write_b32 v206, v115 offset:6912
	v_mul_f32_e32 v106, v84, v0
	v_mul_f32_e32 v107, v85, v1
	v_lshlrev_b32_e32 v108, 16, v102
	v_and_b32_e32 v109, 0xffff0000, v102
	v_fma_f32 v0, v2, v0, -v107
	v_fma_f32 v1, v3, v1, v106
	v_add_f32_e32 v0, v0, v108
	v_add_f32_e32 v1, v1, v109
	v_cvt_pk_bf16_f32 v110, v0, v1
	ds_write_b32 v207, v110 offset:7168
	v_mul_f32_e32 v111, v84, v0
	v_mul_f32_e32 v112, v85, v1
	v_lshlrev_b32_e32 v113, 16, v103
	v_and_b32_e32 v114, 0xffff0000, v103
	v_fma_f32 v0, v2, v0, -v112
	v_fma_f32 v1, v3, v1, v111
	v_add_f32_e32 v0, v0, v113
	v_add_f32_e32 v1, v1, v114
	v_cvt_pk_bf16_f32 v115, v0, v1
	ds_write_b32 v208, v115 offset:7424
	v_mul_f32_e32 v106, v84, v0
	v_mul_f32_e32 v107, v85, v1
	v_lshlrev_b32_e32 v108, 16, v104
	v_and_b32_e32 v109, 0xffff0000, v104
	v_fma_f32 v0, v2, v0, -v107
	v_fma_f32 v1, v3, v1, v106
	v_add_f32_e32 v0, v0, v108
	v_add_f32_e32 v1, v1, v109
	v_cvt_pk_bf16_f32 v110, v0, v1
	ds_write_b32 v209, v110 offset:7680
	v_mul_f32_e32 v111, v84, v0
	v_mul_f32_e32 v112, v85, v1
	v_lshlrev_b32_e32 v113, 16, v105
	v_and_b32_e32 v114, 0xffff0000, v105
	v_fma_f32 v0, v2, v0, -v112
	v_fma_f32 v1, v3, v1, v111
	v_add_f32_e32 v0, v0, v113
	v_add_f32_e32 v1, v1, v114
	v_cvt_pk_bf16_f32 v115, v0, v1
	ds_write_b32 v210, v115 offset:7936
	s_waitcnt lgkmcnt(0)
	ds_read_b128 v[52:55], v87
	ds_read_b128 v[56:59], v92
	v_or_b32_e32 v97, s70, v72
	v_lshl_add_u32 v98, v97, 2, s18
	s_mov_b32 s70, 32
	s_waitcnt lgkmcnt(1)
	v_mfma_f32_16x16x32_bf16 v[52:55], v[52:55], v[36:39], 0
	s_waitcnt lgkmcnt(0)
	v_mfma_f32_16x16x32_bf16 v[52:55], v[56:59], v[40:43], v[52:55]
	ds_read_b128 v[56:59], v93
	s_waitcnt lgkmcnt(0)
	v_mfma_f32_16x16x32_bf16 v[52:55], v[56:59], v[44:47], v[52:55]
	ds_read_b128 v[56:59], v94
	s_waitcnt lgkmcnt(0)
	v_mfma_f32_16x16x32_bf16 v[52:55], v[56:59], v[48:51], v[52:55]
	v_or_b32_e32 v56, s12, v97
	v_ashrrev_i32_e32 v57, 31, v56
	v_lshlrev_b64 v[100:101], 11, v[56:57]
	v_or_b32_e32 v100, v100, v86
	v_lshl_add_u64 v[56:57], v[100:101], 2, s[60:61]
	s_nop 15
	s_nop 15
	v_lshl_add_u64 v[100:101], v[100:101], 1, s[64:65]
	v_mul_f32_e32 v99, v83, v126
	ds_read_b128 v[56:59], v98 offset:16384
	s_waitcnt lgkmcnt(0)
	v_fma_f32 v52, v99, v56, v52
	v_mul_f32_e32 v56, 0x3d372713, v52
	v_mul_f32_e32 v56, v52, v56
	v_fma_f32 v56, v52, v56, v52
	v_mul_f32_e32 v56, 0x3f4c422a, v56
	v_add_f32_e32 v56, v56, v56
	v_mul_f32_e32 v56, 0x3fb8aa3b, v56
	v_exp_f32_e32 v56, v56
	s_nop 0
	v_add_f32_e32 v56, 1.0, v56
	v_div_scale_f32 v99, s[4:5], v56, v56, 1.0
	v_rcp_f32_e32 v102, v99
	s_nop 0
	v_fma_f32 v103, -v99, v102, 1.0
	v_fmac_f32_e32 v102, v103, v102
	v_div_scale_f32 v103, vcc, 1.0, v56, 1.0
	v_mul_f32_e32 v104, v103, v102
	v_fma_f32 v105, -v99, v104, v103
	v_fmac_f32_e32 v104, v105, v102
	v_fma_f32 v99, -v99, v104, v103
	v_div_fmas_f32 v99, v99, v102, v104
	v_div_fixup_f32 v56, v99, v56, 1.0
	v_sub_f32_e32 v56, 1.0, v56
	v_mul_f32_e32 v52, v52, v56
	v_bfe_u32 v56, v52, 16, 1
	v_add3_u32 v52, v52, v56, s75
	global_store_short_d16_hi v[100:101], v52, off
	v_or_b32_e32 v100, s54, v97
	v_ashrrev_i32_e32 v101, 31, v100
	v_lshlrev_b64 v[100:101], 11, v[100:101]
	v_or_b32_e32 v100, v100, v86
	v_lshl_add_u64 v[102:103], v[100:101], 2, s[60:61]
	v_mul_f32_e32 v52, v83, v127
	v_fma_f32 v52, v52, v57, v53
	v_mul_f32_e32 v53, 0x3d372713, v52
	v_mul_f32_e32 v53, v52, v53
	v_fma_f32 v53, v52, v53, v52
	v_mul_f32_e32 v53, 0x3f4c422a, v53
	v_add_f32_e32 v53, v53, v53
	v_mul_f32_e32 v53, 0x3fb8aa3b, v53
	v_exp_f32_e32 v53, v53
	s_nop 0
	v_add_f32_e32 v53, 1.0, v53
	v_div_scale_f32 v56, s[4:5], v53, v53, 1.0
	v_rcp_f32_e32 v57, v56
	s_nop 0
	v_fma_f32 v99, -v56, v57, 1.0
	v_fmac_f32_e32 v57, v99, v57
	v_div_scale_f32 v99, vcc, 1.0, v53, 1.0
	v_mul_f32_e32 v102, v99, v57
	v_fma_f32 v103, -v56, v102, v99
	v_fmac_f32_e32 v102, v103, v57
	v_fma_f32 v56, -v56, v102, v99
	v_div_fmas_f32 v56, v56, v57, v102
	v_div_fixup_f32 v53, v56, v53, 1.0
	v_sub_f32_e32 v53, 1.0, v53
	v_mul_f32_e32 v52, v52, v53
	v_bfe_u32 v53, v52, 16, 1
	v_add3_u32 v56, v52, v53, s75
	v_lshl_add_u64 v[52:53], v[100:101], 1, s[64:65]
	global_store_short_d16_hi v[52:53], v56, off
	v_or_b32_e32 v52, s55, v97
	v_ashrrev_i32_e32 v53, 31, v52
	v_lshlrev_b64 v[52:53], 11, v[52:53]
	v_or_b32_e32 v52, v52, v86
	v_lshl_add_u64 v[56:57], v[52:53], 2, s[60:61]
	v_lshl_add_u64 v[52:53], v[52:53], 1, s[64:65]
	v_mul_f32_e32 v56, v83, v128
	v_fma_f32 v54, v56, v58, v54
	v_mul_f32_e32 v56, 0x3d372713, v54
; #define LAS __attribute__((address_space(3)))
; __device__ __forceinline__ unsigned f2bf(float f) { unsigned u = __builtin_bit_cast(unsigned, f); return (u + 0x7fffu + ((u >> 16) & 1u)) >> 16; }
; __device__ __forceinline__ float gelu_tanh(float v) { const float z = 0.7978845608028654f * (v + 0.044715f * v * v * v); return v * (1.0f - 1.0f / (1.0f + __expf(2.0f * z))); }
; template <int PASS> __device__ __forceinline__ void ssm_phase(int j, LAS unsigned char* lds, int lane, int wave) { KARGS;
;     ...
;                         for (int ks = 0; ks < 4; ++ks) { const bf16x8 hf = *(const LAS bf16x8*)(hL + (16 * lt + fr) * 256 + (((4 * ks + fq) ^ fr) << 4)); y = __builtin_amdgcn_mfma_f32_16x16x32_bf16(hf, cf[ks], y, 0, 0, 0); }
;                         asm volatile("s_nop 15\n\ts_nop 15" : "+v"(y));
;                         const int ch = 16 * g + fr;
; #pragma unroll
;                         for (int r = 0; r < 4; ++r) { const int l = 32 * half + 16 * lt + 4 * fq + r; const size_t t = (size_t)(64 * c + l);
;                             const float v = y[r] + dd * X[t * D + ch] * rsL[l];
;                             GL[t * D + ch] = (bf16_t)f2bf(gelu_tanh(v)); }
	v_mul_f32_e32 v56, v54, v56
	v_fma_f32 v56, v54, v56, v54
	v_mul_f32_e32 v56, 0x3f4c422a, v56
	v_add_f32_e32 v56, v56, v56
	v_mul_f32_e32 v56, 0x3fb8aa3b, v56
	v_exp_f32_e32 v56, v56
	s_nop 0
	v_add_f32_e32 v56, 1.0, v56
	v_div_scale_f32 v57, s[4:5], v56, v56, 1.0
	v_rcp_f32_e32 v58, v57
	s_nop 0
	v_fma_f32 v99, -v57, v58, 1.0
	v_fmac_f32_e32 v58, v99, v58
	v_div_scale_f32 v99, vcc, 1.0, v56, 1.0
	v_mul_f32_e32 v100, v99, v58
	v_fma_f32 v101, -v57, v100, v99
	v_fmac_f32_e32 v100, v101, v58
	v_fma_f32 v57, -v57, v100, v99
	v_div_fmas_f32 v57, v57, v58, v100
	v_div_fixup_f32 v56, v57, v56, 1.0
	v_sub_f32_e32 v56, 1.0, v56
	v_mul_f32_e32 v54, v54, v56
	v_bfe_u32 v56, v54, 16, 1
	v_add3_u32 v54, v54, v56, s75
	global_store_short_d16_hi v[52:53], v54, off
	v_or_b32_e32 v52, s68, v97
	v_ashrrev_i32_e32 v53, 31, v52
	v_lshlrev_b64 v[52:53], 11, v[52:53]
	v_or_b32_e32 v52, v52, v86
	v_lshl_add_u64 v[56:57], v[52:53], 2, s[60:61]
	v_lshl_add_u64 v[52:53], v[52:53], 1, s[64:65]
	v_mul_f32_e32 v54, v83, v129
	v_fmac_f32_e32 v55, v54, v59
	v_mul_f32_e32 v54, 0x3d372713, v55
	v_mul_f32_e32 v54, v55, v54
	v_fma_f32 v54, v55, v54, v55
	v_mul_f32_e32 v54, 0x3f4c422a, v54
	v_add_f32_e32 v54, v54, v54
	v_mul_f32_e32 v54, 0x3fb8aa3b, v54
	v_exp_f32_e32 v54, v54
	s_nop 0
	v_add_f32_e32 v54, 1.0, v54
	v_div_scale_f32 v56, s[4:5], v54, v54, 1.0
	v_rcp_f32_e32 v57, v56
	s_nop 0
	v_fma_f32 v58, -v56, v57, 1.0
	v_fmac_f32_e32 v57, v58, v57
	v_div_scale_f32 v58, vcc, 1.0, v54, 1.0
	v_mul_f32_e32 v59, v58, v57
	v_fma_f32 v99, -v56, v59, v58
	v_fmac_f32_e32 v59, v99, v57
	v_fma_f32 v56, -v56, v59, v58
	v_div_fmas_f32 v56, v56, v57, v59
	v_div_fixup_f32 v54, v56, v54, 1.0
	v_sub_f32_e32 v54, 1.0, v54
	v_mul_f32_e32 v54, v55, v54
	v_bfe_u32 v55, v54, 16, 1
	v_add3_u32 v54, v54, v55, s75
	global_store_short_d16_hi v[52:53], v54, off
	ds_read_b128 v[52:55], v87 offset:4096
	ds_read_b128 v[56:59], v92 offset:4096
	s_waitcnt lgkmcnt(1)
	v_mfma_f32_16x16x32_bf16 v[52:55], v[52:55], v[36:39], 0
	s_waitcnt lgkmcnt(0)
	v_mfma_f32_16x16x32_bf16 v[52:55], v[56:59], v[40:43], v[52:55]
	ds_read_b128 v[56:59], v93 offset:4096
	s_waitcnt lgkmcnt(0)
	v_mfma_f32_16x16x32_bf16 v[52:55], v[56:59], v[44:47], v[52:55]
	ds_read_b128 v[56:59], v94 offset:4096
	s_waitcnt lgkmcnt(0)
	v_mfma_f32_16x16x32_bf16 v[52:55], v[56:59], v[48:51], v[52:55]
	v_or_b32_e32 v56, s13, v97
	v_ashrrev_i32_e32 v57, 31, v56
	v_lshlrev_b64 v[100:101], 11, v[56:57]
	v_or_b32_e32 v100, v100, v86
	v_lshl_add_u64 v[56:57], v[100:101], 2, s[60:61]
	s_nop 15
	s_nop 15
	v_mul_f32_e32 v99, v83, v130
	ds_read_b128 v[56:59], v98 offset:16448
	s_waitcnt lgkmcnt(0)
; #define LAS __attribute__((address_space(3)))
; __device__ __forceinline__ unsigned f2bf(float f) { unsigned u = __builtin_bit_cast(unsigned, f); return (u + 0x7fffu + ((u >> 16) & 1u)) >> 16; }
; __device__ __forceinline__ float gelu_tanh(float v) { const float z = 0.7978845608028654f * (v + 0.044715f * v * v * v); return v * (1.0f - 1.0f / (1.0f + __expf(2.0f * z))); }
; template <int PASS> __device__ __forceinline__ void ssm_phase(int j, LAS unsigned char* lds, int lane, int wave) { KARGS;
;     ...
;                         for (int ks = 0; ks < 4; ++ks) { const bf16x8 hf = *(const LAS bf16x8*)(hL + (16 * lt + fr) * 256 + (((4 * ks + fq) ^ fr) << 4)); y = __builtin_amdgcn_mfma_f32_16x16x32_bf16(hf, cf[ks], y, 0, 0, 0); }
;                         asm volatile("s_nop 15\n\ts_nop 15" : "+v"(y));
;                         const int ch = 16 * g + fr;
; #pragma unroll
;                         for (int r = 0; r < 4; ++r) { const int l = 32 * half + 16 * lt + 4 * fq + r; const size_t t = (size_t)(64 * c + l);
;                             const float v = y[r] + dd * X[t * D + ch] * rsL[l];
;                             GL[t * D + ch] = (bf16_t)f2bf(gelu_tanh(v)); }
;                     }
	v_fma_f32 v52, v99, v56, v52
	v_mul_f32_e32 v56, 0x3d372713, v52
	v_mul_f32_e32 v56, v52, v56
	v_fma_f32 v56, v52, v56, v52
	v_mul_f32_e32 v56, 0x3f4c422a, v56
	v_add_f32_e32 v56, v56, v56
	v_mul_f32_e32 v56, 0x3fb8aa3b, v56
	v_exp_f32_e32 v56, v56
	s_nop 0
	v_add_f32_e32 v56, 1.0, v56
	v_div_scale_f32 v98, s[4:5], v56, v56, 1.0
	v_rcp_f32_e32 v99, v98
	s_nop 0
	v_fma_f32 v102, -v98, v99, 1.0
	v_fmac_f32_e32 v99, v102, v99
	v_div_scale_f32 v102, vcc, 1.0, v56, 1.0
	v_mul_f32_e32 v103, v102, v99
	v_fma_f32 v104, -v98, v103, v102
	v_fmac_f32_e32 v103, v104, v99
	v_fma_f32 v98, -v98, v103, v102
	v_div_fmas_f32 v98, v98, v99, v103
	v_div_fixup_f32 v56, v98, v56, 1.0
	v_sub_f32_e32 v56, 1.0, v56
	v_mul_f32_e32 v52, v52, v56
	v_bfe_u32 v56, v52, 16, 1
	v_add3_u32 v52, v52, v56, s75
	v_lshl_add_u64 v[98:99], v[100:101], 1, s[64:65]
	global_store_short_d16_hi v[98:99], v52, off
	v_or_b32_e32 v98, s77, v97
	v_ashrrev_i32_e32 v99, 31, v98
	v_lshlrev_b64 v[98:99], 11, v[98:99]
	v_or_b32_e32 v98, v98, v86
	v_lshl_add_u64 v[100:101], v[98:99], 2, s[60:61]
	v_mul_f32_e32 v52, v83, v131
	v_fma_f32 v52, v52, v57, v53
	v_mul_f32_e32 v53, 0x3d372713, v52
	v_mul_f32_e32 v53, v52, v53
	v_fma_f32 v53, v52, v53, v52
	v_mul_f32_e32 v53, 0x3f4c422a, v53
	v_add_f32_e32 v53, v53, v53
	v_mul_f32_e32 v53, 0x3fb8aa3b, v53
	v_exp_f32_e32 v53, v53
	s_nop 0
	v_add_f32_e32 v53, 1.0, v53
	v_div_scale_f32 v56, s[4:5], v53, v53, 1.0
	v_rcp_f32_e32 v57, v56
	s_nop 0
	v_fma_f32 v100, -v56, v57, 1.0
	v_fmac_f32_e32 v57, v100, v57
	v_div_scale_f32 v100, vcc, 1.0, v53, 1.0
	v_mul_f32_e32 v101, v100, v57
	v_fma_f32 v102, -v56, v101, v100
	v_fmac_f32_e32 v101, v102, v57
	v_fma_f32 v56, -v56, v101, v100
	v_div_fmas_f32 v56, v56, v57, v101
	v_div_fixup_f32 v53, v56, v53, 1.0
	v_sub_f32_e32 v53, 1.0, v53
	v_mul_f32_e32 v52, v52, v53
	v_bfe_u32 v53, v52, 16, 1
	v_add3_u32 v56, v52, v53, s75
	v_lshl_add_u64 v[52:53], v[98:99], 1, s[64:65]
	global_store_short_d16_hi v[52:53], v56, off
	v_or_b32_e32 v52, s80, v97
	v_ashrrev_i32_e32 v53, 31, v52
	v_lshlrev_b64 v[52:53], 11, v[52:53]
	v_or_b32_e32 v52, v52, v86
	v_lshl_add_u64 v[56:57], v[52:53], 2, s[60:61]
	v_lshl_add_u64 v[52:53], v[52:53], 1, s[64:65]
	v_mul_f32_e32 v56, v83, v132
	v_fma_f32 v54, v56, v58, v54
	v_mul_f32_e32 v56, 0x3d372713, v54
	v_mul_f32_e32 v56, v54, v56
	v_fma_f32 v56, v54, v56, v54
	v_mul_f32_e32 v56, 0x3f4c422a, v56
	v_add_f32_e32 v56, v56, v56
	v_mul_f32_e32 v56, 0x3fb8aa3b, v56
	v_exp_f32_e32 v56, v56
	s_nop 0
	v_add_f32_e32 v56, 1.0, v56
	v_div_scale_f32 v57, s[4:5], v56, v56, 1.0
	v_rcp_f32_e32 v58, v57
	s_nop 0
	v_fma_f32 v98, -v57, v58, 1.0
	v_fmac_f32_e32 v58, v98, v58
	v_div_scale_f32 v98, vcc, 1.0, v56, 1.0
	v_mul_f32_e32 v99, v98, v58
	v_fma_f32 v100, -v57, v99, v98
	v_fmac_f32_e32 v99, v100, v58
	v_fma_f32 v57, -v57, v99, v98
	v_div_fmas_f32 v57, v57, v58, v99
	v_div_fixup_f32 v56, v57, v56, 1.0
	v_sub_f32_e32 v56, 1.0, v56
	v_mul_f32_e32 v54, v54, v56
	v_bfe_u32 v56, v54, 16, 1
	v_add3_u32 v54, v54, v56, s75
	global_store_short_d16_hi v[52:53], v54, off
	v_or_b32_e32 v52, s81, v97
	v_ashrrev_i32_e32 v53, 31, v52
	v_lshlrev_b64 v[52:53], 11, v[52:53]
	v_or_b32_e32 v52, v52, v86
	v_lshl_add_u64 v[56:57], v[52:53], 2, s[60:61]
	v_lshl_add_u64 v[52:53], v[52:53], 1, s[64:65]
	v_mul_f32_e32 v54, v83, v133
	v_fmac_f32_e32 v55, v54, v59
	v_mul_f32_e32 v54, 0x3d372713, v55
	v_mul_f32_e32 v54, v55, v54
	v_fma_f32 v54, v55, v54, v55
	v_mul_f32_e32 v54, 0x3f4c422a, v54
	v_add_f32_e32 v54, v54, v54
	v_mul_f32_e32 v54, 0x3fb8aa3b, v54
	v_exp_f32_e32 v54, v54
	s_nop 0
	v_add_f32_e32 v54, 1.0, v54
	v_div_scale_f32 v56, s[4:5], v54, v54, 1.0
	v_rcp_f32_e32 v57, v56
	s_mov_b64 s[4:5], 0
	v_fma_f32 v58, -v56, v57, 1.0
	v_fmac_f32_e32 v57, v58, v57
	v_div_scale_f32 v58, vcc, 1.0, v54, 1.0
	v_mul_f32_e32 v59, v58, v57
	v_fma_f32 v97, -v56, v59, v58
	v_fmac_f32_e32 v59, v97, v57
	v_fma_f32 v56, -v56, v59, v58
	v_div_fmas_f32 v56, v56, v57, v59
	v_div_fixup_f32 v54, v56, v54, 1.0
	v_sub_f32_e32 v54, 1.0, v54
	v_mul_f32_e32 v54, v55, v54
	v_bfe_u32 v55, v54, 16, 1
	v_add3_u32 v54, v54, v55, s75
	global_store_short_d16_hi v[52:53], v54, off
	s_waitcnt lgkmcnt(0)
	v_mov_b64_e32 v[126:127], v[236:237]
	v_mov_b64_e32 v[128:129], v[238:239]
	v_mov_b64_e32 v[130:131], v[240:241]
	v_mov_b64_e32 v[132:133], v[242:243]
	v_mov_b64_e32 v[156:157], v[172:173]
	v_mov_b64_e32 v[158:159], v[174:175]
	v_mov_b64_e32 v[160:161], v[176:177]
	v_mov_b64_e32 v[162:163], v[178:179]
	v_mov_b64_e32 v[164:165], v[180:181]
	v_mov_b64_e32 v[166:167], v[182:183]
	v_mov_b64_e32 v[168:169], v[184:185]
	v_mov_b64_e32 v[170:171], v[186:187]
	s_and_b64 vcc, exec, s[10:11]
	s_cbranch_vccz .LBB0_343
	s_cmpk_lg_i32 s53, 0x7f
	s_cbranch_scc0 .LBB0_354
	s_cmpk_gt_i32 s53, 0x7f
	s_mov_b64 s[12:13], 0
	s_cbranch_scc1 .LBB0_355
	s_and_b64 vcc, exec, s[4:5]
	v_lshlrev_b32_e32 v192, 2, v60
	s_cbranch_vccnz .LBB0_356
